# attention group B epilogue: sub-layer-norm gain loads issued 4 at a time ahead of the stores (4 waits instead of 16 serialized store round trips)
# baseline (speedup 1.0000x reference)
; DI unsigned pk_bf16(float a, float b) { f32x2_t v = {a, b}; bf16x2_t r = __builtin_convertvector(v, bf16x2_t); return __builtin_bit_cast(unsigned, r); }
; DI float shx(float v, int mask) { const int l = olane(); return __builtin_bit_cast(float, __builtin_amdgcn_ds_bpermute(((l ^ mask) & 63) << 2, __builtin_bit_cast(int, v))); }
; DI void attn_phase(const Params& p, const int j, char* lds, const int cidx) {
;     ...
;                 const float lt = l_run + shx(l_run, 32);
;                 const float inv = 1.f / lt;
;                 if (sub == 0) {
; #pragma unroll
;                     for (int dt = 0; dt < 4; ++dt)
; #pragma unroll
;                         for (int i = 0; i < 8; ++i) O0s[(dt * 8 + i) * 512] = pk_bf16(O[dt][2 * i] * inv, O[dt][2 * i + 1] * inv);
;                 } else {
;                     float ss = 0.f;
; #pragma unroll
;                     for (int dt = 0; dt < 4; ++dt)
; #pragma unroll
;                         for (int i = 0; i < 8; ++i) { const unsigned pw = O0s[(dt * 8 + i) * 512];
;                             const float v0 = __uint_as_float(pw << 16) - lam * O[dt][2 * i] * inv, v1 = __uint_as_float(pw & 0xffff0000u) - lam * O[dt][2 * i + 1] * inv;
;                             O[dt][2 * i] = v0; O[dt][2 * i + 1] = v1; ss += v0 * v0 + v1 * v1; }
.LBB0_197:
	v_mbcnt_lo_u32_b32 v32, -1, 0
	v_mbcnt_hi_u32_b32 v32, -1, v32
	v_lshlrev_b64 v[66:67], 11, v[146:147]
	v_lshlrev_b32_e32 v32, 2, v32
	v_bitop3_b32 v32, v32, s78, v199 bitop3:0x6c
	ds_bpermute_b32 v32, v32, v167
	v_lshl_add_u64 v[66:67], s[82:83], 0, v[66:67]
	s_mov_b32 s9, s89
	v_lshl_add_u64 v[74:75], v[66:67], 0, s[8:9]
	v_mov_b32_e32 v73, v10
	s_waitcnt lgkmcnt(0)
	v_add_f32_e32 v32, v167, v32
	v_div_scale_f32 v66, s[4:5], v32, v32, 1.0
	v_rcp_f32_e32 v67, v66
	v_mov_b32_e32 v10, v9
	v_mov_b32_e32 v72, v8
	v_pk_mul_f32 v[8:9], s[18:19], v[10:11]
	v_fma_f32 v68, -v66, v67, 1.0
	v_fmac_f32_e32 v67, v68, v67
	v_div_scale_f32 v68, vcc, 1.0, v32, 1.0
	v_mul_f32_e32 v69, v68, v67
	v_fma_f32 v70, -v66, v69, v68
	v_fmac_f32_e32 v69, v70, v67
	v_fma_f32 v66, -v66, v69, v68
	v_div_fmas_f32 v66, v66, v67, v69
	ds_read2st64_b32 v[68:69], v160 offset0:208 offset1:216
	ds_read2st64_b32 v[70:71], v161 offset0:224 offset1:232
	v_div_fixup_f32 v66, v66, v32, 1.0
	v_pk_mul_f32 v[72:73], s[18:19], v[72:73]
	v_lshlrev_b32_e32 v32, 1, v138
	s_waitcnt lgkmcnt(0)
	v_lshlrev_b32_e32 v78, 16, v68
	v_and_b32_e32 v79, 0xffff0000, v68
	v_lshlrev_b32_e32 v82, 16, v69
	v_and_b32_e32 v83, 0xffff0000, v69
	ds_read2st64_b32 v[68:69], v160 offset0:224 offset1:232
	v_pk_mul_f32 v[34:35], s[18:19], v[34:35]
	v_pk_mul_f32 v[16:17], s[18:19], v[16:17]
	v_pk_mul_f32 v[36:37], s[18:19], v[36:37]
	v_pk_mul_f32 v[18:19], s[18:19], v[18:19]
	s_waitcnt lgkmcnt(0)
	v_lshlrev_b32_e32 v76, 16, v68
	v_and_b32_e32 v77, 0xffff0000, v68
	v_lshlrev_b32_e32 v80, 16, v69
	v_and_b32_e32 v81, 0xffff0000, v69
	ds_read2st64_b32 v[68:69], v160 offset0:240 offset1:248
	v_pk_mul_f32 v[2:3], s[18:19], v[2:3]
	v_pk_mul_f32 v[0:1], s[18:19], v[0:1]
	v_pk_mul_f32 v[4:5], s[18:19], v[4:5]
	s_waitcnt lgkmcnt(0)
	v_lshlrev_b32_e32 v84, 16, v68
	v_and_b32_e32 v85, 0xffff0000, v68
	v_lshlrev_b32_e32 v88, 16, v69
	v_and_b32_e32 v89, 0xffff0000, v69
	ds_read2st64_b32 v[68:69], v161 offset0:48 offset1:56
	s_waitcnt lgkmcnt(0)
	v_lshlrev_b32_e32 v86, 16, v68
	v_and_b32_e32 v87, 0xffff0000, v68
	v_lshlrev_b32_e32 v90, 16, v69
	v_and_b32_e32 v91, 0xffff0000, v69
	ds_read2st64_b32 v[68:69], v161 offset0:64 offset1:72
	s_waitcnt lgkmcnt(0)
	v_lshlrev_b32_e32 v92, 16, v68
	v_and_b32_e32 v93, 0xffff0000, v68
	v_lshlrev_b32_e32 v96, 16, v69
	v_and_b32_e32 v97, 0xffff0000, v69
	ds_read2st64_b32 v[68:69], v161 offset0:80 offset1:88
	s_waitcnt lgkmcnt(0)
	v_lshlrev_b32_e32 v94, 16, v68
	v_and_b32_e32 v95, 0xffff0000, v68
	v_lshlrev_b32_e32 v98, 16, v69
	v_and_b32_e32 v99, 0xffff0000, v69
	ds_read2st64_b32 v[68:69], v161 offset0:96 offset1:104
	s_waitcnt lgkmcnt(0)
	v_lshlrev_b32_e32 v100, 16, v68
	v_and_b32_e32 v101, 0xffff0000, v68
	v_lshlrev_b32_e32 v104, 16, v69
	v_and_b32_e32 v105, 0xffff0000, v69
	ds_read2st64_b32 v[68:69], v161 offset0:112 offset1:120
	s_waitcnt lgkmcnt(0)
	v_lshlrev_b32_e32 v102, 16, v68
	v_and_b32_e32 v103, 0xffff0000, v68
	v_lshlrev_b32_e32 v106, 16, v69
	v_and_b32_e32 v107, 0xffff0000, v69
	ds_read2st64_b32 v[68:69], v161 offset0:128 offset1:136
	s_waitcnt lgkmcnt(0)
	v_lshlrev_b32_e32 v108, 16, v68
	v_and_b32_e32 v109, 0xffff0000, v68
	v_lshlrev_b32_e32 v112, 16, v69
	v_and_b32_e32 v113, 0xffff0000, v69
	ds_read2st64_b32 v[68:69], v161 offset0:144 offset1:152
	s_waitcnt lgkmcnt(0)
	v_lshlrev_b32_e32 v110, 16, v68
	v_and_b32_e32 v111, 0xffff0000, v68
	s_waitcnt vmcnt(0)
	v_lshlrev_b32_e32 v114, 16, v69
	v_and_b32_e32 v115, 0xffff0000, v69
	ds_read2st64_b32 v[68:69], v161 offset0:160 offset1:168
	s_waitcnt lgkmcnt(0)
	v_lshlrev_b32_e32 v116, 16, v68
	v_and_b32_e32 v117, 0xffff0000, v68
	v_lshlrev_b32_e32 v120, 16, v69
	v_and_b32_e32 v121, 0xffff0000, v69
	ds_read2st64_b32 v[68:69], v161 offset0:176 offset1:184
	s_waitcnt lgkmcnt(0)
	v_lshlrev_b32_e32 v118, 16, v68
	v_and_b32_e32 v119, 0xffff0000, v68
	v_lshlrev_b32_e32 v122, 16, v69
	v_and_b32_e32 v123, 0xffff0000, v69
	ds_read2st64_b32 v[68:69], v161 offset0:192 offset1:200
	s_waitcnt lgkmcnt(0)
	v_lshlrev_b32_e32 v126, 16, v68
	v_and_b32_e32 v127, 0xffff0000, v68
	v_lshlrev_b32_e32 v132, 16, v69
	v_and_b32_e32 v133, 0xffff0000, v69
	ds_read2st64_b32 v[68:69], v161 offset0:208 offset1:216
	v_pk_fma_f32 v[2:3], v[2:3], v[66:67], v[132:133] op_sel_hi:[1,0,1] neg_lo:[1,0,0] neg_hi:[1,0,0]
	s_waitcnt lgkmcnt(0)
	v_lshlrev_b32_e32 v124, 16, v68
	v_and_b32_e32 v125, 0xffff0000, v68
	v_lshlrev_b32_e32 v128, 16, v69
	v_and_b32_e32 v129, 0xffff0000, v69
	v_lshlrev_b32_e32 v69, 16, v71
	v_lshlrev_b32_e32 v68, 16, v70
	v_and_b32_e32 v71, 0xffff0000, v71
	v_and_b32_e32 v70, 0xffff0000, v70
	v_pk_fma_f32 v[70:71], v[8:9], v[66:67], v[70:71] op_sel_hi:[1,0,1] neg_lo:[1,0,0] neg_hi:[1,0,0]
	v_pk_fma_f32 v[68:69], v[72:73], v[66:67], v[68:69] op_sel_hi:[1,0,1] neg_lo:[1,0,0] neg_hi:[1,0,0]
	v_pk_mul_f32 v[8:9], v[70:71], v[70:71]
	v_mov_b32_e32 v72, v12
	v_pk_fma_f32 v[130:131], v[68:69], v[68:69], v[8:9]
	ds_read2st64_b32 v[8:9], v161 offset0:240 offset1:248
	v_mov_b32_e32 v73, v14
	v_pk_mul_f32 v[72:73], s[18:19], v[72:73]
	v_mov_b32_e32 v14, v13
	v_pk_fma_f32 v[4:5], v[4:5], v[66:67], v[124:125] op_sel_hi:[1,0,1] neg_lo:[1,0,0] neg_hi:[1,0,0]
	s_waitcnt lgkmcnt(0)
; DI unsigned pk_bf16(float a, float b) { f32x2_t v = {a, b}; bf16x2_t r = __builtin_convertvector(v, bf16x2_t); return __builtin_bit_cast(unsigned, r); }
; DI float shx(float v, int mask) { const int l = olane(); return __builtin_bit_cast(float, __builtin_amdgcn_ds_bpermute(((l ^ mask) & 63) << 2, __builtin_bit_cast(int, v))); }
; DI void attn_phase(const Params& p, const int j, char* lds, const int cidx) {
;     ...
;                         for (int i = 0; i < 8; ++i) { const unsigned pw = O0s[(dt * 8 + i) * 512];
;                             const float v0 = __uint_as_float(pw << 16) - lam * O[dt][2 * i] * inv, v1 = __uint_as_float(pw & 0xffff0000u) - lam * O[dt][2 * i + 1] * inv;
;                             O[dt][2 * i] = v0; O[dt][2 * i + 1] = v1; ss += v0 * v0 + v1 * v1; }
;                     ss += shx(ss, 32);
;                     const float rs = rsqrtf(ss * (1.f / 128.f) + EPS) * (1.f - lambda_init);
;                     bf16_t* dst = MIX + tokq * DM + 512 + h * 128;
; #pragma unroll
;                     for (int dt = 0; dt < 4; ++dt)
; #pragma unroll
;                         for (int g = 0; g < 4; ++g) { const int dv = 32 * dt + 8 * g + 4 * hh; const f32x4 gn = *(const f32x4*)(subln + dv);
;                             u32x2 o; o[0] = pk_bf16(O[dt][4 * g] * rs * gn[0], O[dt][4 * g + 1] * rs * gn[1]); o[1] = pk_bf16(O[dt][4 * g + 2] * rs * gn[2], O[dt][4 * g + 3] * rs * gn[3]);
;                             *(u32x2*)(dst + dv) = o; }
	v_lshlrev_b32_e32 v11, 16, v9
	v_lshlrev_b32_e32 v10, 16, v8
	v_pk_fma_f32 v[72:73], v[72:73], v[66:67], v[10:11] op_sel_hi:[1,0,1] neg_lo:[1,0,0] neg_hi:[1,0,0]
	v_and_b32_e32 v9, 0xffff0000, v9
	v_and_b32_e32 v8, 0xffff0000, v8
	v_pk_mul_f32 v[10:11], s[18:19], v[14:15]
	v_pk_mul_f32 v[14:15], s[18:19], v[52:53]
	v_pk_fma_f32 v[12:13], v[10:11], v[66:67], v[8:9] op_sel_hi:[1,0,1] neg_lo:[1,0,0] neg_hi:[1,0,0]
	v_pk_fma_f32 v[82:83], v[14:15], v[66:67], v[82:83] op_sel_hi:[1,0,1] neg_lo:[1,0,0] neg_hi:[1,0,0]
	v_pk_mul_f32 v[8:9], v[12:13], v[12:13]
	v_pk_mul_f32 v[14:15], s[18:19], v[50:51]
	v_pk_fma_f32 v[134:135], v[72:73], v[72:73], v[8:9]
	v_mbcnt_lo_u32_b32 v8, -1, 0
	v_mbcnt_hi_u32_b32 v8, -1, v8
	v_pk_mul_f32 v[50:51], s[18:19], v[56:57]
	v_lshlrev_b32_e32 v8, 2, v8
	v_bitop3_b32 v145, v8, s78, v199 bitop3:0x6c
	global_load_dwordx4 v[236:239], v[140:141], off
	global_load_dwordx4 v[240:243], v[140:141], off offset:32
	global_load_dwordx4 v[244:247], v[140:141], off offset:64
	global_load_dwordx4 v[248:251], v[140:141], off offset:96
	v_pk_fma_f32 v[78:79], v[14:15], v[66:67], v[78:79] op_sel_hi:[1,0,1] neg_lo:[1,0,0] neg_hi:[1,0,0]
	v_lshl_add_u64 v[14:15], v[74:75], 0, v[32:33]
	v_pk_fma_f32 v[74:75], v[50:51], v[66:67], v[80:81] op_sel_hi:[1,0,1] neg_lo:[1,0,0] neg_hi:[1,0,0]
	v_pk_mul_f32 v[50:51], s[18:19], v[54:55]
	v_pk_fma_f32 v[54:55], v[36:37], v[66:67], v[96:97] op_sel_hi:[1,0,1] neg_lo:[1,0,0] neg_hi:[1,0,0]
	v_pk_fma_f32 v[80:81], v[50:51], v[66:67], v[76:77] op_sel_hi:[1,0,1] neg_lo:[1,0,0] neg_hi:[1,0,0]
	v_pk_mul_f32 v[50:51], s[18:19], v[60:61]
	v_pk_fma_f32 v[60:61], v[34:35], v[66:67], v[92:93] op_sel_hi:[1,0,1] neg_lo:[1,0,0] neg_hi:[1,0,0]
	v_pk_fma_f32 v[76:77], v[50:51], v[66:67], v[88:89] op_sel_hi:[1,0,1] neg_lo:[1,0,0] neg_hi:[1,0,0]
	v_pk_mul_f32 v[50:51], s[18:19], v[58:59]
	v_pk_mul_f32 v[34:35], s[18:19], v[40:41]
	v_pk_fma_f32 v[84:85], v[50:51], v[66:67], v[84:85] op_sel_hi:[1,0,1] neg_lo:[1,0,0] neg_hi:[1,0,0]
	v_pk_mul_f32 v[50:51], s[18:19], v[64:65]
	v_pk_fma_f32 v[36:37], v[18:19], v[66:67], v[112:113] op_sel_hi:[1,0,1] neg_lo:[1,0,0] neg_hi:[1,0,0]
	v_pk_fma_f32 v[58:59], v[50:51], v[66:67], v[90:91] op_sel_hi:[1,0,1] neg_lo:[1,0,0] neg_hi:[1,0,0]
	v_pk_mul_f32 v[50:51], s[18:19], v[62:63]
	v_pk_mul_f32 v[18:19], s[18:19], v[28:29]
	v_pk_fma_f32 v[62:63], v[50:51], v[66:67], v[86:87] op_sel_hi:[1,0,1] neg_lo:[1,0,0] neg_hi:[1,0,0]
	v_pk_fma_f32 v[50:51], v[34:35], v[66:67], v[98:99] op_sel_hi:[1,0,1] neg_lo:[1,0,0] neg_hi:[1,0,0]
	v_pk_mul_f32 v[34:35], s[18:19], v[38:39]
	v_pk_mul_f32 v[136:137], v[82:83], v[82:83]
	v_pk_fma_f32 v[56:57], v[34:35], v[66:67], v[94:95] op_sel_hi:[1,0,1] neg_lo:[1,0,0] neg_hi:[1,0,0]
	v_pk_mul_f32 v[34:35], s[18:19], v[44:45]
	v_pk_mul_f32 v[146:147], v[78:79], v[78:79]
	v_pk_fma_f32 v[44:45], v[34:35], v[66:67], v[104:105] op_sel_hi:[1,0,1] neg_lo:[1,0,0] neg_hi:[1,0,0]
	v_pk_mul_f32 v[34:35], s[18:19], v[42:43]
	v_pk_fma_f32 v[42:43], v[16:17], v[66:67], v[108:109] op_sel_hi:[1,0,1] neg_lo:[1,0,0] neg_hi:[1,0,0]
	v_pk_fma_f32 v[52:53], v[34:35], v[66:67], v[100:101] op_sel_hi:[1,0,1] neg_lo:[1,0,0] neg_hi:[1,0,0]
	v_pk_mul_f32 v[34:35], s[18:19], v[48:49]
	v_pk_mul_f32 v[16:17], s[18:19], v[22:23]
	v_pk_fma_f32 v[40:41], v[34:35], v[66:67], v[106:107] op_sel_hi:[1,0,1] neg_lo:[1,0,0] neg_hi:[1,0,0]
	v_pk_mul_f32 v[34:35], s[18:19], v[46:47]
	v_pk_fma_f32 v[22:23], v[18:19], v[66:67], v[118:119] op_sel_hi:[1,0,1] neg_lo:[1,0,0] neg_hi:[1,0,0]
	v_pk_fma_f32 v[46:47], v[34:35], v[66:67], v[102:103] op_sel_hi:[1,0,1] neg_lo:[1,0,0] neg_hi:[1,0,0]
	v_pk_fma_f32 v[34:35], v[16:17], v[66:67], v[114:115] op_sel_hi:[1,0,1] neg_lo:[1,0,0] neg_hi:[1,0,0]
	v_pk_mul_f32 v[16:17], s[18:19], v[20:21]
	v_mov_b32_e32 v28, v23
	v_pk_fma_f32 v[38:39], v[16:17], v[66:67], v[110:111] op_sel_hi:[1,0,1] neg_lo:[1,0,0] neg_hi:[1,0,0]
	v_pk_mul_f32 v[16:17], s[18:19], v[26:27]
	v_mov_b32_e32 v18, v22
	v_pk_fma_f32 v[20:21], v[16:17], v[66:67], v[120:121] op_sel_hi:[1,0,1] neg_lo:[1,0,0] neg_hi:[1,0,0]
	v_pk_mul_f32 v[16:17], s[18:19], v[24:25]
	v_pk_mul_f32 v[150:151], v[80:81], v[80:81]
	v_pk_fma_f32 v[24:25], v[16:17], v[66:67], v[116:117] op_sel_hi:[1,0,1] neg_lo:[1,0,0] neg_hi:[1,0,0]
	v_pk_mul_f32 v[16:17], s[18:19], v[30:31]
	v_mov_b32_e32 v31, v3
	v_pk_fma_f32 v[16:17], v[16:17], v[66:67], v[122:123] op_sel_hi:[1,0,1] neg_lo:[1,0,0] neg_hi:[1,0,0]
	v_add_f32_e32 v32, v136, v137
	v_mov_b32_e32 v29, v17
	v_mov_b32_e32 v19, v16
	v_pk_mul_f32 v[28:29], v[28:29], v[28:29]
	v_pk_mul_f32 v[148:149], v[74:75], v[74:75]
	v_pk_fma_f32 v[28:29], v[18:19], v[18:19], v[28:29]
	v_pk_fma_f32 v[18:19], v[0:1], v[66:67], v[126:127] op_sel_hi:[1,0,1] neg_lo:[1,0,0] neg_hi:[1,0,0]
	v_mov_b32_e32 v1, v2
	v_mov_b32_e32 v30, v19
	v_mov_b32_e32 v0, v18
	v_pk_mul_f32 v[30:31], v[30:31], v[30:31]
	v_pk_mul_f32 v[152:153], v[84:85], v[84:85]
	v_pk_fma_f32 v[30:31], v[0:1], v[0:1], v[30:31]
	v_pk_mul_f32 v[0:1], s[18:19], v[6:7]
	v_mov_b32_e32 v6, v4
	v_pk_fma_f32 v[0:1], v[0:1], v[66:67], v[128:129] op_sel_hi:[1,0,1] neg_lo:[1,0,0] neg_hi:[1,0,0]
	v_mov_b32_e32 v66, v5
	v_mov_b32_e32 v67, v1
	v_mov_b32_e32 v7, v0
	v_pk_mul_f32 v[66:67], v[66:67], v[66:67]
	v_pk_mul_f32 v[88:89], v[76:77], v[76:77]
	v_pk_fma_f32 v[6:7], v[6:7], v[6:7], v[66:67]
	v_add_f32_e32 v66, v146, v147
	v_add_f32_e32 v32, v66, v32
	v_add_f32_e32 v66, v150, v151
	v_add_f32_e32 v32, v32, v66
	v_add_f32_e32 v66, v148, v149
	v_add_f32_e32 v32, v32, v66
	v_add_f32_e32 v66, v152, v153
	v_pk_mul_f32 v[86:87], v[62:63], v[62:63]
	v_add_f32_e32 v32, v32, v66
	v_add_f32_e32 v66, v88, v89
	v_pk_mul_f32 v[64:65], v[58:59], v[58:59]
; DI unsigned pk_bf16(float a, float b) { f32x2_t v = {a, b}; bf16x2_t r = __builtin_convertvector(v, bf16x2_t); return __builtin_bit_cast(unsigned, r); }
; DI float shx(float v, int mask) { const int l = olane(); return __builtin_bit_cast(float, __builtin_amdgcn_ds_bpermute(((l ^ mask) & 63) << 2, __builtin_bit_cast(int, v))); }
; DI void attn_phase(const Params& p, const int j, char* lds, const int cidx) {
;     ...
;                     ss += shx(ss, 32);
;                     const float rs = rsqrtf(ss * (1.f / 128.f) + EPS) * (1.f - lambda_init);
;                     bf16_t* dst = MIX + tokq * DM + 512 + h * 128;
; #pragma unroll
;                     for (int dt = 0; dt < 4; ++dt)
; #pragma unroll
;                         for (int g = 0; g < 4; ++g) { const int dv = 32 * dt + 8 * g + 4 * hh; const f32x4 gn = *(const f32x4*)(subln + dv);
;                             u32x2 o; o[0] = pk_bf16(O[dt][4 * g] * rs * gn[0], O[dt][4 * g + 1] * rs * gn[1]); o[1] = pk_bf16(O[dt][4 * g + 2] * rs * gn[2], O[dt][4 * g + 3] * rs * gn[3]);
;                             *(u32x2*)(dst + dv) = o; }
	v_add_f32_e32 v32, v32, v66
	v_add_f32_e32 v66, v86, v87
	v_pk_mul_f32 v[92:93], v[60:61], v[60:61]
	v_add_f32_e32 v32, v32, v66
	v_add_f32_e32 v64, v64, v65
	v_pk_mul_f32 v[90:91], v[54:55], v[54:55]
	v_add_f32_e32 v32, v32, v64
	v_add_f32_e32 v64, v92, v93
	v_pk_mul_f32 v[94:95], v[56:57], v[56:57]
	v_add_f32_e32 v32, v32, v64
	v_add_f32_e32 v64, v90, v91
	v_pk_mul_f32 v[96:97], v[50:51], v[50:51]
	v_add_f32_e32 v32, v32, v64
	v_add_f32_e32 v64, v94, v95
	v_pk_mul_f32 v[100:101], v[52:53], v[52:53]
	v_add_f32_e32 v32, v32, v64
	v_add_f32_e32 v64, v96, v97
	v_pk_mul_f32 v[98:99], v[44:45], v[44:45]
	v_add_f32_e32 v32, v32, v64
	v_add_f32_e32 v64, v100, v101
	v_pk_mul_f32 v[102:103], v[46:47], v[46:47]
	v_add_f32_e32 v32, v32, v64
	v_add_f32_e32 v64, v98, v99
	v_pk_mul_f32 v[48:49], v[40:41], v[40:41]
	v_add_f32_e32 v32, v32, v64
	v_add_f32_e32 v64, v102, v103
	v_pk_mul_f32 v[106:107], v[42:43], v[42:43]
	v_add_f32_e32 v32, v32, v64
	v_add_f32_e32 v48, v48, v49
	v_pk_mul_f32 v[104:105], v[36:37], v[36:37]
	v_add_f32_e32 v32, v32, v48
	v_add_f32_e32 v48, v106, v107
	v_pk_mul_f32 v[110:111], v[38:39], v[38:39]
	v_add_f32_e32 v32, v32, v48
	v_add_f32_e32 v48, v104, v105
	v_pk_mul_f32 v[108:109], v[34:35], v[34:35]
	v_add_f32_e32 v32, v32, v48
	v_add_f32_e32 v48, v110, v111
	v_pk_mul_f32 v[112:113], v[24:25], v[24:25]
	v_add_f32_e32 v32, v32, v48
	v_add_f32_e32 v48, v108, v109
	v_pk_mul_f32 v[26:27], v[20:21], v[20:21]
	v_add_f32_e32 v32, v32, v48
	v_add_f32_e32 v48, v112, v113
	v_add_f32_e32 v32, v32, v48
	v_add_f32_e32 v26, v26, v27
	v_add_f32_e32 v26, v32, v26
	v_add_f32_e32 v26, v26, v28
	v_add_f32_e32 v26, v26, v29
	v_add_f32_e32 v26, v26, v30
	v_add_f32_e32 v26, v26, v31
	v_add_f32_e32 v6, v26, v6
	v_add_f32_e32 v6, v6, v7
	v_add_f32_e32 v6, v6, v130
	v_add_f32_e32 v6, v6, v131
	v_add_f32_e32 v6, v6, v134
	v_add_f32_e32 v6, v6, v135
	ds_bpermute_b32 v7, v145, v6
	s_waitcnt lgkmcnt(0)
	v_add_f32_e32 v6, v6, v7
	v_fmamk_f32 v6, v6, 0x3c000000, v197
	v_cmp_gt_f32_e32 vcc, s79, v6
	v_mul_f32_e32 v7, 0x4b800000, v6
	s_nop 0
	v_cndmask_b32_e32 v6, v6, v7, vcc
	v_rsq_f32_e32 v6, v6
	s_nop 0
	v_mul_f32_e32 v7, 0x45800000, v6
	v_cndmask_b32_e32 v6, v6, v7, vcc
	v_mul_f32_e32 v6, v162, v6
	v_pk_mul_f32 v[26:27], v[78:79], v[6:7] op_sel_hi:[1,0]
	v_pk_mul_f32 v[24:25], v[24:25], v[6:7] op_sel_hi:[1,0]
	s_waitcnt vmcnt(0)
	v_pk_mul_f32 v[8:9], v[236:237], v[26:27]
	v_pk_mul_f32 v[26:27], v[82:83], v[6:7] op_sel_hi:[1,0]
	v_cvt_pk_bf16_f32 v8, v8, v9
	v_pk_mul_f32 v[10:11], v[238:239], v[26:27]
	v_pk_mul_f32 v[26:27], v[80:81], v[6:7] op_sel_hi:[1,0]
	v_cvt_pk_bf16_f32 v9, v10, v11
	flat_store_dwordx2 v[14:15], v[8:9] offset:1024
	v_pk_mul_f32 v[20:21], v[20:21], v[6:7] op_sel_hi:[1,0]
	v_pk_mul_f32 v[16:17], v[16:17], v[6:7] op_sel_hi:[1,0]
	v_pk_mul_f32 v[2:3], v[2:3], v[6:7] op_sel_hi:[1,0]
	v_pk_mul_f32 v[0:1], v[0:1], v[6:7] op_sel_hi:[1,0]
	v_pk_mul_f32 v[8:9], v[240:241], v[26:27]
	v_pk_mul_f32 v[26:27], v[74:75], v[6:7] op_sel_hi:[1,0]
	v_cvt_pk_bf16_f32 v8, v8, v9
	v_pk_mul_f32 v[10:11], v[242:243], v[26:27]
	v_pk_mul_f32 v[26:27], v[84:85], v[6:7] op_sel_hi:[1,0]
	v_cvt_pk_bf16_f32 v9, v10, v11
	flat_store_dwordx2 v[14:15], v[8:9] offset:1040
	v_pk_mul_f32 v[8:9], v[244:245], v[26:27]
	v_pk_mul_f32 v[26:27], v[76:77], v[6:7] op_sel_hi:[1,0]
	v_cvt_pk_bf16_f32 v8, v8, v9
	v_pk_mul_f32 v[10:11], v[246:247], v[26:27]
	v_pk_mul_f32 v[26:27], v[62:63], v[6:7] op_sel_hi:[1,0]
	v_cvt_pk_bf16_f32 v9, v10, v11
	flat_store_dwordx2 v[14:15], v[8:9] offset:1056
	v_pk_mul_f32 v[8:9], v[248:249], v[26:27]
	v_pk_mul_f32 v[26:27], v[58:59], v[6:7] op_sel_hi:[1,0]
	v_cvt_pk_bf16_f32 v8, v8, v9
	v_pk_mul_f32 v[10:11], v[250:251], v[26:27]
	v_pk_mul_f32 v[26:27], v[60:61], v[6:7] op_sel_hi:[1,0]
	v_cvt_pk_bf16_f32 v9, v10, v11
	flat_store_dwordx2 v[14:15], v[8:9] offset:1072
	global_load_dwordx4 v[236:239], v[140:141], off offset:128
	global_load_dwordx4 v[240:243], v[140:141], off offset:160
	global_load_dwordx4 v[244:247], v[140:141], off offset:192
	global_load_dwordx4 v[248:251], v[140:141], off offset:224
	s_waitcnt vmcnt(0)
; DI unsigned pk_bf16(float a, float b) { f32x2_t v = {a, b}; bf16x2_t r = __builtin_convertvector(v, bf16x2_t); return __builtin_bit_cast(unsigned, r); }
; DI void attn_phase(const Params& p, const int j, char* lds, const int cidx) {
;     ...
;                     for (int dt = 0; dt < 4; ++dt)
; #pragma unroll
;                         for (int g = 0; g < 4; ++g) { const int dv = 32 * dt + 8 * g + 4 * hh; const f32x4 gn = *(const f32x4*)(subln + dv);
;                             u32x2 o; o[0] = pk_bf16(O[dt][4 * g] * rs * gn[0], O[dt][4 * g + 1] * rs * gn[1]); o[1] = pk_bf16(O[dt][4 * g + 2] * rs * gn[2], O[dt][4 * g + 3] * rs * gn[3]);
;                             *(u32x2*)(dst + dv) = o; }
	v_pk_mul_f32 v[8:9], v[236:237], v[26:27]
	v_pk_mul_f32 v[26:27], v[54:55], v[6:7] op_sel_hi:[1,0]
	v_cvt_pk_bf16_f32 v8, v8, v9
	v_pk_mul_f32 v[10:11], v[238:239], v[26:27]
	v_pk_mul_f32 v[26:27], v[56:57], v[6:7] op_sel_hi:[1,0]
	v_cvt_pk_bf16_f32 v9, v10, v11
	flat_store_dwordx2 v[14:15], v[8:9] offset:1088
	v_pk_mul_f32 v[8:9], v[240:241], v[26:27]
	v_pk_mul_f32 v[26:27], v[50:51], v[6:7] op_sel_hi:[1,0]
	v_cvt_pk_bf16_f32 v8, v8, v9
	v_pk_mul_f32 v[10:11], v[242:243], v[26:27]
	v_pk_mul_f32 v[26:27], v[52:53], v[6:7] op_sel_hi:[1,0]
	v_cvt_pk_bf16_f32 v9, v10, v11
	flat_store_dwordx2 v[14:15], v[8:9] offset:1104
	v_pk_mul_f32 v[8:9], v[244:245], v[26:27]
	v_pk_mul_f32 v[26:27], v[44:45], v[6:7] op_sel_hi:[1,0]
	v_cvt_pk_bf16_f32 v8, v8, v9
	v_pk_mul_f32 v[10:11], v[246:247], v[26:27]
	v_pk_mul_f32 v[26:27], v[46:47], v[6:7] op_sel_hi:[1,0]
	v_cvt_pk_bf16_f32 v9, v10, v11
	flat_store_dwordx2 v[14:15], v[8:9] offset:1120
	v_pk_mul_f32 v[8:9], v[26:27], v[248:249]
	v_pk_mul_f32 v[26:27], v[40:41], v[6:7] op_sel_hi:[1,0]
	v_cvt_pk_bf16_f32 v8, v8, v9
	v_pk_mul_f32 v[10:11], v[26:27], v[250:251]
	v_pk_mul_f32 v[26:27], v[42:43], v[6:7] op_sel_hi:[1,0]
	v_cvt_pk_bf16_f32 v9, v10, v11
	flat_store_dwordx2 v[14:15], v[8:9] offset:1136
	global_load_dwordx4 v[236:239], v[140:141], off offset:256
	global_load_dwordx4 v[240:243], v[140:141], off offset:288
	global_load_dwordx4 v[244:247], v[140:141], off offset:320
	global_load_dwordx4 v[248:251], v[140:141], off offset:352
	s_waitcnt vmcnt(0)
	v_pk_mul_f32 v[8:9], v[26:27], v[236:237]
	v_pk_mul_f32 v[26:27], v[36:37], v[6:7] op_sel_hi:[1,0]
	v_cvt_pk_bf16_f32 v8, v8, v9
	v_pk_mul_f32 v[10:11], v[26:27], v[238:239]
	v_pk_mul_f32 v[26:27], v[38:39], v[6:7] op_sel_hi:[1,0]
	v_cvt_pk_bf16_f32 v9, v10, v11
	flat_store_dwordx2 v[14:15], v[8:9] offset:1152
	v_pk_mul_f32 v[8:9], v[26:27], v[240:241]
	v_pk_mul_f32 v[26:27], v[34:35], v[6:7] op_sel_hi:[1,0]
	v_cvt_pk_bf16_f32 v8, v8, v9
	v_pk_mul_f32 v[10:11], v[26:27], v[242:243]
	s_nop 0
	v_cvt_pk_bf16_f32 v9, v10, v11
	flat_store_dwordx2 v[14:15], v[8:9] offset:1168
	v_pk_mul_f32 v[8:9], v[24:25], v[244:245]
	v_pk_mul_f32 v[10:11], v[20:21], v[246:247]
	v_cvt_pk_bf16_f32 v8, v8, v9
	v_cvt_pk_bf16_f32 v9, v10, v11
	flat_store_dwordx2 v[14:15], v[8:9] offset:1184
	v_pk_mul_f32 v[20:21], v[22:23], v[6:7] op_sel_hi:[1,0]
	v_pk_mul_f32 v[10:11], v[16:17], v[250:251]
	v_pk_mul_f32 v[8:9], v[20:21], v[248:249]
	v_pk_mul_f32 v[16:17], v[18:19], v[6:7] op_sel_hi:[1,0]
	v_cvt_pk_bf16_f32 v8, v8, v9
	v_cvt_pk_bf16_f32 v9, v10, v11
	flat_store_dwordx2 v[14:15], v[8:9] offset:1200
	global_load_dwordx4 v[236:239], v[140:141], off offset:384
	global_load_dwordx4 v[240:243], v[140:141], off offset:416
	global_load_dwordx4 v[244:247], v[140:141], off offset:448
	global_load_dwordx4 v[248:251], v[140:141], off offset:480
	s_waitcnt vmcnt(0)
	v_pk_mul_f32 v[8:9], v[16:17], v[236:237]
	v_pk_mul_f32 v[2:3], v[2:3], v[238:239]
	v_cvt_pk_bf16_f32 v8, v8, v9
	v_cvt_pk_bf16_f32 v9, v2, v3
	flat_store_dwordx2 v[14:15], v[8:9] offset:1216
	v_pk_mul_f32 v[2:3], v[4:5], v[6:7] op_sel_hi:[1,0]
	v_mov_b32_e32 v4, v68
	v_mov_b32_e32 v5, v70
	v_pk_mul_f32 v[4:5], v[4:5], v[6:7] op_sel_hi:[1,0]
	v_mov_b32_e32 v70, v69
	v_pk_mul_f32 v[2:3], v[2:3], v[240:241]
	v_pk_mul_f32 v[0:1], v[0:1], v[242:243]
	v_cvt_pk_bf16_f32 v2, v2, v3
	v_cvt_pk_bf16_f32 v3, v0, v1
	flat_store_dwordx2 v[14:15], v[2:3] offset:1232
	v_pk_mul_f32 v[0:1], v[4:5], v[244:245]
	v_pk_mul_f32 v[4:5], v[70:71], v[6:7] op_sel_hi:[1,0]
	v_cvt_pk_bf16_f32 v0, v0, v1
	v_pk_mul_f32 v[2:3], v[4:5], v[246:247]
	v_mov_b32_e32 v4, v72
	v_cvt_pk_bf16_f32 v1, v2, v3
	flat_store_dwordx2 v[14:15], v[0:1] offset:1248
	v_mov_b32_e32 v5, v12
	v_pk_mul_f32 v[4:5], v[4:5], v[6:7] op_sel_hi:[1,0]
	v_mov_b32_e32 v12, v73
	v_pk_mul_f32 v[0:1], v[4:5], v[248:249]
	v_pk_mul_f32 v[4:5], v[12:13], v[6:7] op_sel_hi:[1,0]
	v_cvt_pk_bf16_f32 v0, v0, v1
	v_pk_mul_f32 v[2:3], v[4:5], v[250:251]
	s_nop 0
	v_cvt_pk_bf16_f32 v1, v2, v3
	flat_store_dwordx2 v[14:15], v[0:1] offset:1264
